# mode0 attn: QK C operand held in a persistent 16-register block (refilled only when bias zone or reference changes) instead of per-tile v_mov prefill; K/V loads back at tile head with SGPR-base addres
# speedup vs baseline: 1.0108x; 1.0006x over previous
; __device__ __forceinline__ float swapmax(float m) { auto rr = __builtin_amdgcn_permlane32_swap(__float_as_uint(m), __float_as_uint(m), false, false); return fmaxf(__uint_as_float(rr[0]), __uint_as_float(rr[1])); }
; #define A2_TILE_BIAS(t, cbv, nearv) do { cbv = 0.f; nearv = (MODE == 2); if (MODE == 0) { const int ks_ = 64 * (t); const int maxrel_ = ks_ + 63 - qslot0, minrel_ = ks_ - (qslot0 + 31); \
;         const bool lf_ = maxrel_ <= -91, rt_ = minrel_ >= 91; cbv = lf_ ? tabL : (rt_ ? tabR : 0.f); nearv = !(lf_ || rt_); } } while (0)
; template <int MODE> __device__ __forceinline__ void attn_unit4(LAS unsigned char* lds, const int uidx, const AttnArgs& A) {
;     ...
;     float mref;
;     { float mx = fmaxf(s0[0], s1[0]);
; #pragma unroll
;       for (int r = 1; r < 16; ++r) mx = fmaxf(mx, fmaxf(s0[r], s1[r]));
;       mx = swapmax(mx) + cbc; mref = fmaxf(mx, -30.0f);
;       const float sh = cbc - mref;
; #pragma unroll
;       for (int r = 0; r < 16; ++r) { s0[r] += sh; s1[r] += sh; } }
;     constexpr bool USE_NEGC = (MODE != 0);
;     f32x16 negc;
;     { float cb1; bool nr1; A2_TILE_BIAS(t0 + 1, cb1, nr1); const float nv = cb1 - mref;
; #pragma unroll
;       for (int r = 0; r < 16; ++r) { n0[r] = nv; n1[r] = nv; negc[r] = nv; } }
;     int vs_prev = 2, vs_cur = 0, vs_next = 1;
; #pragma unroll
;     for (int c = 0; c < 4; ++c) pk[c] = (u32x4){0u, 0u, 0u, 0u};
.LBB0_983:
	v_cndmask_b32_e32 v3, 0, v195, vcc
	v_max_f32_e32 v2, v2, v2
	v_max_f32_e32 v0, v0, v0
	v_cndmask_b32_e64 v3, v3, v194, s[0:1]
	v_max_f32_e32 v0, v0, v2
	v_add_f32_e32 v0, v3, v0
	v_max_f32_e32 v197, 0xc1f00000, v0
	v_cndmask_b32_e64 v0, 0, v195, s[6:7]
	v_cndmask_b32_e64 v0, v0, v194, s[4:5]
	s_movk_i32 s0, 0x140
	v_and_b32_e32 v177, 63, v19
	v_sub_f32_e32 v82, v0, v197
	v_sub_f32_e32 v0, v3, v197
	v_mov_b32_e32 v19, v10
	v_mov_b32_e32 v4, v11
	v_mov_b32_e32 v5, v12
	v_mov_b32_e32 v6, v13
	v_mov_b32_e32 v7, v14
	v_mov_b32_e32 v8, v15
	v_mov_b32_e32 v9, v16
	v_mad_u64_u32 v[178:179], s[0:1], v22, s0, v[20:21]
	s_mulk_i32 s37, 0x2080
	v_pk_add_f32 v[2:3], v[18:19], v[0:1] op_sel_hi:[1,0]
	v_pk_add_f32 v[4:5], v[4:5], v[0:1] op_sel_hi:[1,0]
	v_pk_add_f32 v[6:7], v[6:7], v[0:1] op_sel_hi:[1,0]
	v_pk_add_f32 v[8:9], v[8:9], v[0:1] op_sel_hi:[1,0]
	v_add_f32_e32 v81, v17, v0
	s_add_i32 s70, s71, 0x7a
	s_addk_i32 s71, 0xffb9
	v_or_b32_e32 v0, s37, v181
	s_lshl_b32 s0, s36, 7
	v_sub_u32_e32 v0, v0, v21
	s_add_u32 s1, s73, s8
	v_subrev_u32_e32 v0, s52, v0
	s_addc_u32 s4, s53, s9
	v_mov_b32_e32 v14, v1
	v_mov_b32_e32 v15, v1
	v_mov_b32_e32 v98, v2
	v_mov_b32_e32 v99, v2
	v_mov_b32_e32 v100, v2
	v_mov_b32_e32 v101, v2
	v_mov_b32_e32 v102, v2
	v_mov_b32_e32 v103, v2
	v_mov_b32_e32 v104, v2
	v_mov_b32_e32 v105, v2
	v_mov_b32_e32 v106, v2
	v_mov_b32_e32 v107, v2
	v_mov_b32_e32 v108, v2
	v_mov_b32_e32 v109, v2
	v_mov_b32_e32 v110, v2
	v_mov_b32_e32 v111, v2
	v_mov_b32_e32 v112, v2
	v_mov_b32_e32 v113, v2
	v_mov_b32_e32 v66, v2
	v_mov_b32_e32 v67, v2
	v_mov_b32_e32 v68, v2
	v_mov_b32_e32 v69, v2
	v_mov_b32_e32 v70, v2
	v_mov_b32_e32 v71, v2
	v_mov_b32_e32 v72, v2
	v_mov_b32_e32 v73, v2
	v_mov_b32_e32 v74, v3
	v_mov_b32_e32 v75, v4
	v_mov_b32_e32 v76, v5
	v_mov_b32_e32 v77, v6
	v_mov_b32_e32 v78, v7
	v_mov_b32_e32 v79, v8
	v_mov_b32_e32 v80, v9
	v_subrev_u32_e32 v179, s0, v0
	s_add_u32 s8, s16, s1
	v_mov_b32_e32 v0, v1
	v_mov_b32_e32 v2, v1
	v_mov_b32_e32 v3, v1
	v_mov_b32_e32 v4, v1
	v_mov_b32_e32 v5, v1
	v_mov_b32_e32 v6, v1
	v_mov_b32_e32 v7, v1
	v_mov_b32_e32 v8, v1
	v_mov_b32_e32 v9, v1
	v_mov_b32_e32 v10, v1
	v_mov_b32_e32 v11, v1
	v_mov_b32_e32 v12, v1
	v_mov_b32_e32 v13, v1
	v_mov_b64_e32 v[64:65], v[14:15]
	v_mov_b64_e32 v[48:49], v[14:15]
	v_mov_b64_e32 v[32:33], v[14:15]
	s_addc_u32 s9, s17, s4
	s_sub_i32 s1, s37, s52
	v_mov_b64_e32 v[62:63], v[12:13]
	v_mov_b64_e32 v[60:61], v[10:11]
	v_mov_b64_e32 v[58:59], v[8:9]
	v_mov_b64_e32 v[56:57], v[6:7]
	v_mov_b64_e32 v[54:55], v[4:5]
	v_mov_b64_e32 v[52:53], v[2:3]
	v_mov_b64_e32 v[50:51], v[0:1]
	v_mov_b64_e32 v[46:47], v[12:13]
	v_mov_b64_e32 v[44:45], v[10:11]
	v_mov_b64_e32 v[42:43], v[8:9]
	v_mov_b64_e32 v[40:41], v[6:7]
	v_mov_b64_e32 v[38:39], v[4:5]
	v_mov_b64_e32 v[36:37], v[2:3]
	v_mov_b64_e32 v[34:35], v[0:1]
	v_mov_b64_e32 v[30:31], v[12:13]
	v_mov_b64_e32 v[28:29], v[10:11]
	v_mov_b64_e32 v[26:27], v[8:9]
	v_mov_b64_e32 v[24:25], v[6:7]
	v_mov_b64_e32 v[22:23], v[4:5]
	v_mov_b64_e32 v[20:21], v[2:3]
	v_mov_b64_e32 v[18:19], v[0:1]
	v_mov_b64_e32 v[16:17], v[14:15]
	s_mov_b32 s72, 1
	s_sub_i32 s73, s1, s0
	s_mov_b32 s74, 0
	s_mov_b32 s0, 2
	v_mov_b32_e32 v180, 1.0
	v_mov_b32_e32 v198, 0
	s_movk_i32 s75, 0x100
	v_mov_b32_e32 v142, 0
	v_mov_b32_e32 v143, 0
	v_mov_b32_e32 v144, 0
	v_mov_b32_e32 v145, 0
	v_mov_b32_e32 v138, 0
	v_mov_b32_e32 v139, 0
	v_mov_b32_e32 v140, 0
	v_mov_b32_e32 v141, 0
	v_mov_b32_e32 v134, 0
	v_mov_b32_e32 v135, 0
	v_mov_b32_e32 v136, 0
	v_mov_b32_e32 v137, 0
	v_mov_b32_e32 v130, 0
	v_mov_b32_e32 v131, 0
	v_mov_b32_e32 v132, 0
	v_mov_b32_e32 v133, 0
	v_mov_b64_e32 v[14:15], v[12:13]
	v_mov_b64_e32 v[12:13], v[10:11]
	v_mov_b64_e32 v[10:11], v[8:9]
	v_mov_b64_e32 v[8:9], v[6:7]
	v_mov_b64_e32 v[6:7], v[4:5]
	v_mov_b64_e32 v[4:5], v[2:3]
	v_mov_b64_e32 v[2:3], v[0:1]
	v_mov_b32_e32 v0, 1.0
	s_add_u32 s84, s8, s88
	s_addc_u32 s85, s9, 0
	s_add_u32 s98, s8, s67
	s_addc_u32 s99, s9, 0
	v_mov_b32_e32 v228, v82
	v_mov_b32_e32 v229, v82
	v_mov_b32_e32 v230, v82
	v_mov_b32_e32 v231, v82
	v_mov_b32_e32 v232, v82
	v_mov_b32_e32 v233, v82
	v_mov_b32_e32 v234, v82
	v_mov_b32_e32 v235, v82
	v_mov_b32_e32 v236, v82
	v_mov_b32_e32 v237, v82
	v_mov_b32_e32 v238, v82
	v_mov_b32_e32 v239, v82
	v_mov_b32_e32 v240, v82
	v_mov_b32_e32 v241, v82
	v_mov_b32_e32 v242, v82
	v_mov_b32_e32 v243, v82
	s_mov_b32 s76, 1
	s_mov_b32 s77, s74
	s_mov_b32 s74, s0
	v_cmp_neq_f32_e32 vcc, 1.0, v180
	s_cbranch_vccz .LBB0_985

.LBB0_985:
	s_waitcnt lgkmcnt(3)
	v_mfma_f32_32x32x16_bf16 v[50:65], v[158:161], v[142:145], v[50:65]
	s_add_i32 s52, s73, s75
	s_add_i32 s0, s75, 0xffffff80
	s_add_i32 s37, s52, 0xffffff80
	s_cmp_lt_i32 s0, s70
	s_cselect_b64 s[6:7], -1, 0
	s_sub_i32 s0, s52, 64
	s_cmpk_gt_i32 s0, 0xff66
	s_cselect_b64 s[0:1], -1, 0
	s_add_i32 s36, s52, 0xffffffa1
	s_cmpk_gt_i32 s36, 0x5a
	s_cselect_b64 s[4:5], -1, 0
	s_cmp_gt_u32 s76, 1
	s_cselect_b32 s53, s74, s77
	s_mulk_i32 s53, 0x5000
	s_cmpk_gt_i32 s37, 0xff66
	v_add_u32_e32 v180, s53, v192
	s_cselect_b64 s[78:79], -1, 0
	v_add_u32_e32 v199, 0xc800, v180
	s_and_b64 s[6:7], s[78:79], s[6:7]
	ds_read_b64_tr_b16 v[200:201], v180 offset:56320
	ds_read_b64_tr_b16 v[202:203], v180 offset:58880
	s_mul_i32 s78, s72, 0x5000
	s_add_i32 s37, s78, 0
	s_waitcnt lgkmcnt(4)
	v_mfma_f32_32x32x16_bf16 v[34:49], v[154:157], v[142:145], v[34:49]
	ds_read_b64_tr_b16 v[204:205], v180 offset:56384
	ds_read_b64_tr_b16 v[206:207], v180 offset:58944
	global_load_dwordx4 v[162:165], v168, s[84:85] offset:1024
	global_load_dwordx4 v[158:161], v170, s[84:85] offset:1024
	s_waitcnt lgkmcnt(5)
	v_mfma_f32_32x32x16_bf16 v[18:33], v[150:153], v[142:145], v[18:33]
	ds_read_b64_tr_b16 v[208:209], v180 offset:56448
	ds_read_b64_tr_b16 v[210:211], v180 offset:59008
	global_load_dwordx4 v[150:153], v168, s[98:99] offset:2048
	global_load_dwordx4 v[154:157], v170, s[98:99] offset:2048
	s_waitcnt lgkmcnt(6)
	v_mfma_f32_32x32x16_bf16 v[2:17], v[146:149], v[142:145], v[2:17]
	ds_read_b64_tr_b16 v[220:221], v180 offset:56512
	ds_read_b64_tr_b16 v[222:223], v180 offset:59072
	s_waitcnt lgkmcnt(6)
	v_mfma_f32_32x32x16_bf16 v[50:65], v[200:203], v[138:141], v[50:65]
	ds_read_b64_tr_b16 v[146:147], v180 offset:61440
	ds_read_b64_tr_b16 v[148:149], v180 offset:64000
	v_exp_f32_e32 v98, v98
	v_exp_f32_e32 v99, v99
	v_add_f32_e32 v142, 0, v98
	v_add_f32_e32 v143, v99, v142
	v_cvt_pk_bf16_f32 v142, v98, v99
	s_waitcnt lgkmcnt(6)
	v_mfma_f32_32x32x16_bf16 v[34:49], v[204:207], v[138:141], v[34:49]
	ds_read_b64_tr_b16 v[200:201], v180 offset:61504
	ds_read_b64_tr_b16 v[202:203], v180 offset:64064
	v_exp_f32_e32 v98, v100
	v_exp_f32_e32 v100, v101
	v_add_f32_e32 v99, v98, v143
	v_add_f32_e32 v144, v100, v99
	v_cvt_pk_bf16_f32 v143, v98, v100
	s_waitcnt lgkmcnt(6)
	v_mfma_f32_32x32x16_bf16 v[18:33], v[208:211], v[138:141], v[18:33]
	ds_read_b64_tr_b16 v[98:99], v180 offset:61568
	ds_read_b64_tr_b16 v[100:101], v180 offset:64128
	v_exp_f32_e32 v102, v102
	s_nop 0
	v_add_f32_e32 v144, v102, v144
	v_exp_f32_e32 v103, v103
	s_waitcnt lgkmcnt(6)
	v_mfma_f32_32x32x16_bf16 v[2:17], v[220:223], v[138:141], v[2:17]
	ds_read_b64_tr_b16 v[204:205], v180 offset:61632
	ds_read_b64_tr_b16 v[206:207], v180 offset:64192
	v_add_f32_e32 v145, v103, v144
	v_cvt_pk_bf16_f32 v144, v102, v103
	v_exp_f32_e32 v102, v104
	s_nop 0
	v_add_f32_e32 v103, v102, v145
	s_waitcnt lgkmcnt(6)
	v_mfma_f32_32x32x16_bf16 v[50:65], v[146:149], v[134:137], v[50:65]
	ds_read_b64_tr_b16 v[208:209], v199 offset:15360
	ds_read_b64_tr_b16 v[210:211], v199 offset:17920
	v_exp_f32_e32 v104, v105
	s_nop 0
	v_add_f32_e32 v138, v104, v103
	v_cvt_pk_bf16_f32 v145, v102, v104
	s_waitcnt lgkmcnt(6)
	v_mfma_f32_32x32x16_bf16 v[34:49], v[200:203], v[134:137], v[34:49]
	ds_read_b64_tr_b16 v[102:103], v199 offset:15424
	ds_read_b64_tr_b16 v[104:105], v199 offset:17984
	v_exp_f32_e32 v106, v106
	v_exp_f32_e32 v107, v107
	v_add_f32_e32 v138, v106, v138
	v_add_f32_e32 v139, v107, v138
	v_cvt_pk_bf16_f32 v138, v106, v107
	s_waitcnt lgkmcnt(6)
	v_mfma_f32_32x32x16_bf16 v[18:33], v[98:101], v[134:137], v[18:33]
	ds_read_b64_tr_b16 v[146:147], v199 offset:15488
	ds_read_b64_tr_b16 v[148:149], v199 offset:18048
	v_exp_f32_e32 v98, v108
	v_exp_f32_e32 v100, v109
	v_add_f32_e32 v99, v98, v139
	v_add_f32_e32 v106, v100, v99
	v_cvt_pk_bf16_f32 v139, v98, v100
	s_waitcnt lgkmcnt(6)
	v_mfma_f32_32x32x16_bf16 v[2:17], v[204:207], v[134:137], v[2:17]
	ds_read_b64_tr_b16 v[98:99], v199 offset:15552
	ds_read_b64_tr_b16 v[100:101], v199 offset:18112
	v_exp_f32_e32 v107, v110
	s_nop 0
	v_add_f32_e32 v106, v107, v106
	v_exp_f32_e32 v108, v111
	s_waitcnt lgkmcnt(6)
	v_mfma_f32_32x32x16_bf16 v[50:65], v[208:211], v[130:133], v[50:65]
	ds_read_b128 v[200:203], v196
	v_cvt_pk_bf16_f32 v140, v107, v108
	v_exp_f32_e32 v107, v112
	v_add_f32_e32 v106, v108, v106
	v_add_f32_e32 v106, v107, v106
	s_waitcnt lgkmcnt(5)
	v_mfma_f32_32x32x16_bf16 v[34:49], v[102:105], v[130:133], v[34:49]
	ds_read_b128 v[204:207], v196 offset:8704
	v_exp_f32_e32 v108, v113
	s_nop 0
	v_add_f32_e32 v106, v108, v106
	v_cvt_pk_bf16_f32 v141, v107, v108
	s_waitcnt lgkmcnt(4)
	v_mfma_f32_32x32x16_bf16 v[18:33], v[146:149], v[130:133], v[18:33]
	ds_read_b128 v[208:211], v196 offset:32
	v_exp_f32_e32 v66, v66
	v_exp_f32_e32 v67, v67
	v_add_f32_e32 v102, v66, v106
	v_add_f32_e32 v102, v67, v102
	v_cvt_pk_bf16_f32 v134, v66, v67
	s_waitcnt lgkmcnt(3)
	v_mfma_f32_32x32x16_bf16 v[2:17], v[98:101], v[130:133], v[2:17]
	ds_read_b128 v[146:149], v196 offset:8736
	v_exp_f32_e32 v66, v68
	v_exp_f32_e32 v68, v69
	v_add_f32_e32 v67, v66, v102
	v_add_f32_e32 v98, v68, v67
	v_cvt_pk_bf16_f32 v135, v66, v68
	v_exp_f32_e32 v70, v70
	ds_read_b128 v[66:69], v196 offset:64
	v_add_f32_e32 v130, v70, v98
	s_waitcnt lgkmcnt(4)
	v_mfma_f32_32x32x16_bf16 v[98:113], v[200:203], v[114:117], v[228:243]
	s_waitcnt lgkmcnt(3)
	v_mfma_f32_32x32x16_bf16 v[82:97], v[204:207], v[114:117], v[228:243]
	ds_read_b128 v[200:203], v196 offset:8768
	v_exp_f32_e32 v71, v71
	s_nop 0
	v_cvt_pk_bf16_f32 v136, v70, v71
	v_exp_f32_e32 v70, v72
	v_add_f32_e32 v130, v71, v130
	v_add_f32_e32 v71, v70, v130
	s_waitcnt lgkmcnt(3)
	v_mfma_f32_32x32x16_bf16 v[98:113], v[208:211], v[118:121], v[98:113]
	ds_read_b128 v[204:207], v196 offset:96
	v_exp_f32_e32 v72, v73
	s_nop 0
	v_add_f32_e32 v130, v72, v71
	v_cvt_pk_bf16_f32 v137, v70, v72
	s_waitcnt lgkmcnt(3)
	v_mfma_f32_32x32x16_bf16 v[82:97], v[146:149], v[118:121], v[82:97]
	ds_read_b128 v[70:73], v196 offset:8800
	v_exp_f32_e32 v74, v74
	v_exp_f32_e32 v75, v75
	v_add_f32_e32 v130, v74, v130
	v_add_f32_e32 v131, v75, v130
	v_cvt_pk_bf16_f32 v130, v74, v75
	s_waitcnt lgkmcnt(3)
	v_mfma_f32_32x32x16_bf16 v[98:113], v[66:69], v[122:125], v[98:113]
	v_exp_f32_e32 v66, v76
	v_exp_f32_e32 v68, v77
	s_waitcnt vmcnt(3)
	ds_write_b128 v190, v[162:165] offset:25600
	s_waitcnt vmcnt(2)
	ds_write_b128 v188, v[158:161] offset:25600
	v_add_f32_e32 v67, v66, v131
	v_cvt_pk_bf16_f32 v131, v66, v68
	v_add_f32_e32 v67, v68, v67
	s_waitcnt lgkmcnt(4)
	v_mfma_f32_32x32x16_bf16 v[82:97], v[200:203], v[122:125], v[82:97]
	v_exp_f32_e32 v66, v78
	s_nop 0
	v_add_f32_e32 v67, v66, v67
	s_waitcnt lgkmcnt(3)
	v_mfma_f32_32x32x16_bf16 v[98:113], v[204:207], v[126:129], v[98:113]
	v_exp_f32_e32 v68, v79
	s_nop 0
	v_cvt_pk_bf16_f32 v132, v66, v68
	v_exp_f32_e32 v66, v80
	v_add_f32_e32 v67, v68, v67
	v_add_u32_e32 v68, s37, v176
	s_waitcnt vmcnt(1)
	ds_write_b128 v68, v[150:153] offset:51200
	v_add_u32_e32 v68, s37, v178
	v_add_f32_e32 v67, v66, v67
	s_waitcnt vmcnt(0)
	ds_write_b128 v68, v[154:157] offset:51200
	s_cmpk_lt_u32 s76, 0x7f
	s_cselect_b32 s84, 0x4d000, 0
	s_add_u32 s84, s84, s88
	s_add_u32 s84, s8, s84
	s_addc_u32 s85, s9, 0
	s_add_u32 s98, s8, s88
	s_addc_u32 s99, s9, 0
	s_waitcnt lgkmcnt(4)
	v_mfma_f32_32x32x16_bf16 v[82:97], v[70:73], v[126:129], v[82:97]
	v_exp_f32_e32 v68, v81
	s_nop 0
	v_add_f32_e32 v199, v68, v67
	v_cvt_pk_bf16_f32 v133, v66, v68
	s_mul_i32 s37, s77, 0x5000
	v_add_u32_e32 v201, s37, v192
	ds_read_b64_tr_b16 v[158:159], v201 offset:51200
	ds_read_b64_tr_b16 v[154:155], v201 offset:51264
	ds_read_b64_tr_b16 v[150:151], v201 offset:51328
	ds_read_b64_tr_b16 v[146:147], v201 offset:51392
	ds_read_b64_tr_b16 v[160:161], v201 offset:53760
	ds_read_b64_tr_b16 v[156:157], v201 offset:53824
	ds_read_b64_tr_b16 v[152:153], v201 offset:53888
	ds_read_b64_tr_b16 v[148:149], v201 offset:53952
	s_andn2_b64 vcc, exec, s[6:7]
	v_add_u32_e32 v200, s75, v179
	s_cbranch_vccnz .LBB0_987
	v_add_u32_e32 v66, 0x80, v200
	v_med3_i32 v67, v66, 0, v216
	v_med3_i32 v66, v66, s46, v217
	v_lshl_add_u32 v68, v66, 2, s15
	v_add_u32_e32 v66, 0x81, v200
	v_med3_i32 v69, v66, 0, v216
	v_med3_i32 v66, v66, s46, v217
	v_lshl_add_u32 v70, v66, 2, s15
	v_add_u32_e32 v66, 0x82, v200
	v_med3_i32 v71, v66, 0, v216
	v_med3_i32 v66, v66, s46, v217
	v_lshl_add_u32 v72, v66, 2, s15
	v_add_u32_e32 v66, 0x83, v200
	v_med3_i32 v73, v66, 0, v216
	v_med3_i32 v66, v66, s46, v217
	v_lshl_add_u32 v67, v67, 2, s15
	v_lshl_add_u32 v69, v69, 2, s15
	v_lshl_add_u32 v71, v71, 2, s15
	v_lshl_add_u32 v73, v73, 2, s15
	v_lshl_add_u32 v74, v66, 2, s15
	ds_read_b32 v66, v67
	ds_read_b32 v68, v68 offset:128
	ds_read_b32 v67, v69
	ds_read_b32 v69, v70 offset:128
	ds_read_b32 v70, v71
	ds_read_b32 v72, v72 offset:128
	ds_read_b32 v71, v73
	ds_read_b32 v73, v74 offset:128
	v_add_u32_e32 v74, 0x88, v200
	v_med3_i32 v75, v74, 0, v216
	v_med3_i32 v74, v74, s46, v217
	v_lshl_add_u32 v76, v74, 2, s15
	v_add_u32_e32 v74, 0x89, v200
	v_med3_i32 v77, v74, 0, v216
	v_med3_i32 v74, v74, s46, v217
	v_lshl_add_u32 v78, v74, 2, s15
	v_add_u32_e32 v74, 0x8a, v200
	v_med3_i32 v79, v74, 0, v216
	v_med3_i32 v74, v74, s46, v217
	v_lshl_add_u32 v80, v74, 2, s15
	v_add_u32_e32 v74, 0x8b, v200
	v_med3_i32 v81, v74, 0, v216
	v_med3_i32 v74, v74, s46, v217
	v_lshl_add_u32 v75, v75, 2, s15
	v_lshl_add_u32 v77, v77, 2, s15
	v_lshl_add_u32 v79, v79, 2, s15
	v_lshl_add_u32 v81, v81, 2, s15
	v_lshl_add_u32 v162, v74, 2, s15
	ds_read_b32 v74, v75
	ds_read_b32 v76, v76 offset:128
	ds_read_b32 v75, v77
	ds_read_b32 v77, v78 offset:128
	ds_read_b32 v78, v79
	ds_read_b32 v80, v80 offset:128
	ds_read_b32 v79, v81
	ds_read_b32 v81, v162 offset:128
	v_add_u32_e32 v162, 0x90, v200
	v_med3_i32 v163, v162, 0, v216
	v_med3_i32 v162, v162, s46, v217
	v_lshl_add_u32 v164, v162, 2, s15
	v_add_u32_e32 v162, 0x91, v200
	v_med3_i32 v165, v162, 0, v216
	v_med3_i32 v162, v162, s46, v217
	v_lshl_add_u32 v180, v162, 2, s15
	v_add_u32_e32 v162, 0x92, v200
	v_med3_i32 v202, v162, 0, v216
	v_med3_i32 v162, v162, s46, v217
	v_add_u32_e32 v207, 0x99, v200
	v_lshl_add_u32 v203, v162, 2, s15
	v_add_u32_e32 v162, 0x93, v200
	v_med3_i32 v208, v207, 0, v216
	v_med3_i32 v207, v207, s46, v217
	v_med3_i32 v204, v162, 0, v216
	v_lshl_add_u32 v214, v207, 2, s15
	v_add_u32_e32 v207, 0x9a, v200
	v_lshl_add_u32 v163, v163, 2, s15
	v_lshl_add_u32 v165, v165, 2, s15
	v_lshl_add_u32 v202, v202, 2, s15
	v_med3_i32 v162, v162, s46, v217
	v_lshl_add_u32 v205, v204, 2, s15
	v_lshl_add_u32 v209, v208, 2, s15
	v_med3_i32 v208, v207, 0, v216
	v_med3_i32 v207, v207, s46, v217
	v_lshl_add_u32 v206, v162, 2, s15
	ds_read_b32 v162, v163
	ds_read_b32 v164, v164 offset:128
	ds_read_b32 v163, v165
	ds_read_b32 v165, v180 offset:128
	ds_read_b32 v202, v202
	ds_read_b32 v204, v203 offset:128
	ds_read_b32 v203, v205
	ds_read_b32 v205, v206 offset:128
	v_add_u32_e32 v180, 0x98, v200
	v_lshl_add_u32 v212, v207, 2, s15
	v_add_u32_e32 v207, 0x9b, v200
	v_med3_i32 v206, v180, 0, v216
	v_lshl_add_u32 v210, v208, 2, s15
	v_med3_i32 v208, v207, 0, v216
	v_med3_i32 v207, v207, s46, v217
	v_med3_i32 v180, v180, s46, v217
	v_lshl_add_u32 v206, v206, 2, s15
	v_lshl_add_u32 v211, v208, 2, s15
	v_lshl_add_u32 v213, v207, 2, s15
	v_lshl_add_u32 v180, v180, 2, s15
	ds_read_b32 v206, v206
	ds_read_b32 v208, v180 offset:128
	ds_read_b32 v210, v210
	ds_read_b32 v211, v211
	ds_read_b32 v207, v209
	ds_read_b32 v213, v213 offset:128
	ds_read_b32 v212, v212 offset:128
	ds_read_b32 v209, v214 offset:128
	s_waitcnt lgkmcnt(4)
	v_pk_add_f32 v[112:113], v[112:113], v[210:211]
	s_waitcnt lgkmcnt(3)
	v_pk_add_f32 v[110:111], v[110:111], v[206:207]
	v_pk_add_f32 v[108:109], v[108:109], v[202:203]
	v_pk_add_f32 v[106:107], v[106:107], v[162:163]
	v_pk_add_f32 v[104:105], v[104:105], v[78:79]
	v_pk_add_f32 v[102:103], v[102:103], v[74:75]
	v_pk_add_f32 v[100:101], v[100:101], v[70:71]
	v_pk_add_f32 v[98:99], v[98:99], v[66:67]
	s_waitcnt lgkmcnt(1)
	v_pk_add_f32 v[96:97], v[96:97], v[212:213]
	s_waitcnt lgkmcnt(0)
	v_pk_add_f32 v[94:95], v[94:95], v[208:209]
	v_pk_add_f32 v[92:93], v[92:93], v[204:205]
	v_pk_add_f32 v[90:91], v[90:91], v[164:165]
	v_pk_add_f32 v[88:89], v[88:89], v[80:81]
	v_pk_add_f32 v[86:87], v[86:87], v[76:77]
	v_pk_add_f32 v[84:85], v[84:85], v[72:73]
	v_pk_add_f32 v[82:83], v[82:83], v[68:69]

.LBB0_990:
	v_cmp_neq_f32_e32 vcc, v66, v228
	s_cbranch_vccz .Lnc_a_skip
	v_mov_b32_e32 v228, v66
	v_mov_b32_e32 v229, v66
	v_mov_b32_e32 v230, v66
	v_mov_b32_e32 v231, v66
	v_mov_b32_e32 v232, v66
	v_mov_b32_e32 v233, v66
	v_mov_b32_e32 v234, v66
	v_mov_b32_e32 v235, v66
	v_mov_b32_e32 v236, v66
	v_mov_b32_e32 v237, v66
	v_mov_b32_e32 v238, v66
	v_mov_b32_e32 v239, v66
	v_mov_b32_e32 v240, v66
	v_mov_b32_e32 v241, v66
	v_mov_b32_e32 v242, v66
	v_mov_b32_e32 v243, v66
.Lnc_a_skip:
	v_cmp_neq_f32_e32 vcc, 1.0, v0
	s_waitcnt lgkmcnt(0)
	s_barrier
	s_cbranch_vccz .LBB0_992
	v_pk_mul_f32 v[64:65], v[0:1], v[64:65] op_sel_hi:[0,1]
	v_pk_mul_f32 v[62:63], v[0:1], v[62:63] op_sel_hi:[0,1]
	v_pk_mul_f32 v[60:61], v[0:1], v[60:61] op_sel_hi:[0,1]
	v_pk_mul_f32 v[58:59], v[0:1], v[58:59] op_sel_hi:[0,1]
	v_pk_mul_f32 v[56:57], v[0:1], v[56:57] op_sel_hi:[0,1]
	v_pk_mul_f32 v[54:55], v[0:1], v[54:55] op_sel_hi:[0,1]
	v_pk_mul_f32 v[52:53], v[0:1], v[52:53] op_sel_hi:[0,1]
	v_pk_mul_f32 v[50:51], v[0:1], v[50:51] op_sel_hi:[0,1]
	v_pk_mul_f32 v[48:49], v[0:1], v[48:49] op_sel_hi:[0,1]
	v_pk_mul_f32 v[46:47], v[0:1], v[46:47] op_sel_hi:[0,1]
	v_pk_mul_f32 v[44:45], v[0:1], v[44:45] op_sel_hi:[0,1]
	v_pk_mul_f32 v[42:43], v[0:1], v[42:43] op_sel_hi:[0,1]
	v_pk_mul_f32 v[40:41], v[0:1], v[40:41] op_sel_hi:[0,1]
	v_pk_mul_f32 v[38:39], v[0:1], v[38:39] op_sel_hi:[0,1]
	v_pk_mul_f32 v[36:37], v[0:1], v[36:37] op_sel_hi:[0,1]
	v_pk_mul_f32 v[34:35], v[0:1], v[34:35] op_sel_hi:[0,1]
	v_pk_mul_f32 v[32:33], v[0:1], v[32:33] op_sel_hi:[0,1]
	v_pk_mul_f32 v[30:31], v[0:1], v[30:31] op_sel_hi:[0,1]
	v_pk_mul_f32 v[28:29], v[0:1], v[28:29] op_sel_hi:[0,1]
	v_pk_mul_f32 v[26:27], v[0:1], v[26:27] op_sel_hi:[0,1]
	v_pk_mul_f32 v[24:25], v[0:1], v[24:25] op_sel_hi:[0,1]
	v_pk_mul_f32 v[22:23], v[0:1], v[22:23] op_sel_hi:[0,1]
	v_pk_mul_f32 v[20:21], v[0:1], v[20:21] op_sel_hi:[0,1]
	v_pk_mul_f32 v[18:19], v[0:1], v[18:19] op_sel_hi:[0,1]
	v_pk_mul_f32 v[16:17], v[0:1], v[16:17] op_sel_hi:[0,1]
	v_pk_mul_f32 v[14:15], v[0:1], v[14:15] op_sel_hi:[0,1]
	v_pk_mul_f32 v[12:13], v[0:1], v[12:13] op_sel_hi:[0,1]
	v_pk_mul_f32 v[10:11], v[0:1], v[10:11] op_sel_hi:[0,1]
	v_pk_mul_f32 v[8:9], v[0:1], v[8:9] op_sel_hi:[0,1]
	v_pk_mul_f32 v[6:7], v[0:1], v[6:7] op_sel_hi:[0,1]
	v_pk_mul_f32 v[4:5], v[0:1], v[4:5] op_sel_hi:[0,1]
	v_pk_mul_f32 v[2:3], v[0:1], v[2:3] op_sel_hi:[0,1]
.LBB0_992:
	v_mfma_f32_32x32x16_bf16 v[50:65], v[158:161], v[142:145], v[50:65]
	s_cmpk_lt_i32 s36, 0x5b
	s_cselect_b64 s[36:37], -1, 0
	s_add_i32 s6, s75, 0xffffff40
	s_addk_i32 s52, 0xff40
	s_cmpk_lt_i32 s52, 0xfea7
	s_cselect_b64 s[4:5], -1, 0
	s_cmp_gt_i32 s6, s71
	s_cselect_b64 s[6:7], -1, 0
	v_add_u32_e32 v210, 0xc800, v201
	s_cmpk_gt_u32 s76, 0x7e
	s_cselect_b64 s[52:53], -1, 0
	ds_read_b64_tr_b16 v[202:203], v201 offset:56320
	ds_read_b64_tr_b16 v[204:205], v201 offset:58880
	s_mul_i32 s79, s74, 0x5000
	s_add_i32 s79, s79, 0
	v_mfma_f32_32x32x16_bf16 v[34:49], v[154:157], v[142:145], v[34:49]
	ds_read_b64_tr_b16 v[206:207], v201 offset:56384
	ds_read_b64_tr_b16 v[208:209], v201 offset:58944
	ds_read_b64_tr_b16 v[220:221], v201 offset:56448
	ds_read_b64_tr_b16 v[222:223], v201 offset:59008
	global_load_dwordx4 v[162:165], v168, s[84:85] offset:1024
	global_load_dwordx4 v[158:161], v170, s[84:85] offset:1024
	v_mfma_f32_32x32x16_bf16 v[18:33], v[150:153], v[142:145], v[18:33]
	global_load_dwordx4 v[150:153], v168, s[98:99] offset:2048
	global_load_dwordx4 v[154:157], v170, s[98:99] offset:2048
	v_mfma_f32_32x32x16_bf16 v[2:17], v[146:149], v[142:145], v[2:17]
	ds_read_b64_tr_b16 v[182:183], v201 offset:56512
	ds_read_b64_tr_b16 v[184:185], v201 offset:59072
	s_waitcnt lgkmcnt(6)
	v_mfma_f32_32x32x16_bf16 v[50:65], v[202:205], v[138:141], v[50:65]
	ds_read_b64_tr_b16 v[146:147], v201 offset:61440
	ds_read_b64_tr_b16 v[148:149], v201 offset:64000
	v_exp_f32_e32 v98, v98
	v_exp_f32_e32 v99, v99
	v_add_f32_e32 v142, 0, v98
	v_add_f32_e32 v143, v99, v142
	v_cvt_pk_bf16_f32 v142, v98, v99
	s_waitcnt lgkmcnt(6)
	v_mfma_f32_32x32x16_bf16 v[34:49], v[206:209], v[138:141], v[34:49]
	ds_read_b64_tr_b16 v[202:203], v201 offset:61504
	ds_read_b64_tr_b16 v[204:205], v201 offset:64064
	v_exp_f32_e32 v98, v100
	v_exp_f32_e32 v100, v101
	v_add_f32_e32 v99, v98, v143
	v_add_f32_e32 v144, v100, v99
	v_cvt_pk_bf16_f32 v143, v98, v100
	s_waitcnt lgkmcnt(6)
	v_mfma_f32_32x32x16_bf16 v[18:33], v[220:223], v[138:141], v[18:33]
	ds_read_b64_tr_b16 v[98:99], v201 offset:61568
	ds_read_b64_tr_b16 v[100:101], v201 offset:64128
	v_exp_f32_e32 v102, v102
	s_nop 0
	v_add_f32_e32 v144, v102, v144
	v_exp_f32_e32 v103, v103
	s_waitcnt lgkmcnt(6)
	v_mfma_f32_32x32x16_bf16 v[2:17], v[182:185], v[138:141], v[2:17]
	ds_read_b64_tr_b16 v[206:207], v201 offset:61632
	ds_read_b64_tr_b16 v[208:209], v201 offset:64192
	v_add_f32_e32 v145, v103, v144
	v_cvt_pk_bf16_f32 v144, v102, v103
	v_exp_f32_e32 v102, v104
	s_nop 0
	v_add_f32_e32 v103, v102, v145
	s_waitcnt lgkmcnt(6)
	v_mfma_f32_32x32x16_bf16 v[50:65], v[146:149], v[134:137], v[50:65]
	ds_read_b64_tr_b16 v[182:183], v210 offset:15360
	ds_read_b64_tr_b16 v[184:185], v210 offset:17920
	v_exp_f32_e32 v104, v105
	s_nop 0
	v_add_f32_e32 v138, v104, v103
	v_cvt_pk_bf16_f32 v145, v102, v104
	s_waitcnt lgkmcnt(6)
	v_mfma_f32_32x32x16_bf16 v[34:49], v[202:205], v[134:137], v[34:49]
	ds_read_b64_tr_b16 v[102:103], v210 offset:15424
	ds_read_b64_tr_b16 v[104:105], v210 offset:17984
	v_exp_f32_e32 v106, v106
	v_exp_f32_e32 v107, v107
	v_add_f32_e32 v138, v106, v138
	v_add_f32_e32 v139, v107, v138
	v_cvt_pk_bf16_f32 v138, v106, v107
	s_waitcnt lgkmcnt(6)
	v_mfma_f32_32x32x16_bf16 v[18:33], v[98:101], v[134:137], v[18:33]
	ds_read_b64_tr_b16 v[146:147], v210 offset:15488
	ds_read_b64_tr_b16 v[148:149], v210 offset:18048
	v_exp_f32_e32 v98, v108
	v_exp_f32_e32 v100, v109
	v_add_f32_e32 v99, v98, v139
	v_add_f32_e32 v106, v100, v99
	v_cvt_pk_bf16_f32 v139, v98, v100
	s_waitcnt lgkmcnt(6)
	v_mfma_f32_32x32x16_bf16 v[2:17], v[206:209], v[134:137], v[2:17]
	ds_read_b64_tr_b16 v[98:99], v210 offset:15552
	ds_read_b64_tr_b16 v[100:101], v210 offset:18112
	v_exp_f32_e32 v107, v110
	s_nop 0
	v_add_f32_e32 v106, v107, v106
	v_exp_f32_e32 v108, v111
	s_waitcnt lgkmcnt(6)
	v_mfma_f32_32x32x16_bf16 v[50:65], v[182:185], v[130:133], v[50:65]
	ds_read_b128 v[202:205], v196 offset:25600
	v_cvt_pk_bf16_f32 v140, v107, v108
	v_exp_f32_e32 v107, v112
	v_add_f32_e32 v106, v108, v106
	v_add_f32_e32 v106, v107, v106
	s_waitcnt lgkmcnt(5)
	v_mfma_f32_32x32x16_bf16 v[34:49], v[102:105], v[130:133], v[34:49]
	ds_read_b128 v[182:185], v196 offset:34304
	v_exp_f32_e32 v108, v113
	s_nop 0
	v_add_f32_e32 v106, v108, v106
	v_cvt_pk_bf16_f32 v141, v107, v108
	s_waitcnt lgkmcnt(4)
	v_mfma_f32_32x32x16_bf16 v[18:33], v[146:149], v[130:133], v[18:33]
	ds_read_b128 v[206:209], v196 offset:25632
	v_exp_f32_e32 v82, v82
	v_exp_f32_e32 v83, v83
	v_add_f32_e32 v102, v82, v106
	v_add_f32_e32 v102, v83, v102
	v_cvt_pk_bf16_f32 v134, v82, v83
	s_waitcnt lgkmcnt(3)
	v_mfma_f32_32x32x16_bf16 v[2:17], v[98:101], v[130:133], v[2:17]
	ds_read_b128 v[146:149], v196 offset:34336
	v_exp_f32_e32 v82, v84
	v_exp_f32_e32 v84, v85
	v_add_f32_e32 v83, v82, v102
	v_add_f32_e32 v98, v84, v83
	v_cvt_pk_bf16_f32 v135, v82, v84
	v_exp_f32_e32 v86, v86
	ds_read_b128 v[82:85], v196 offset:25664
	v_add_f32_e32 v130, v86, v98
	s_waitcnt lgkmcnt(4)
	v_mfma_f32_32x32x16_bf16 v[98:113], v[202:205], v[114:117], v[228:243]
	s_waitcnt lgkmcnt(3)
	v_mfma_f32_32x32x16_bf16 v[66:81], v[182:185], v[114:117], v[228:243]
	ds_read_b128 v[202:205], v196 offset:34368
	v_exp_f32_e32 v87, v87
	s_nop 0
	v_cvt_pk_bf16_f32 v136, v86, v87
	v_exp_f32_e32 v86, v88
	v_add_f32_e32 v130, v87, v130
	v_add_f32_e32 v87, v86, v130
	s_waitcnt lgkmcnt(3)
	v_mfma_f32_32x32x16_bf16 v[98:113], v[206:209], v[118:121], v[98:113]
	ds_read_b128 v[182:185], v196 offset:25696
	v_exp_f32_e32 v88, v89
	s_nop 0
	v_add_f32_e32 v130, v88, v87
	v_cvt_pk_bf16_f32 v137, v86, v88
	s_waitcnt lgkmcnt(3)
	v_mfma_f32_32x32x16_bf16 v[66:81], v[146:149], v[118:121], v[66:81]
	ds_read_b128 v[86:89], v196 offset:34400
	v_exp_f32_e32 v90, v90
	v_exp_f32_e32 v91, v91
	v_add_f32_e32 v130, v90, v130
	v_add_f32_e32 v131, v91, v130
	v_cvt_pk_bf16_f32 v130, v90, v91
	s_waitcnt lgkmcnt(3)
	v_mfma_f32_32x32x16_bf16 v[98:113], v[82:85], v[122:125], v[98:113]
	v_exp_f32_e32 v82, v92
	v_exp_f32_e32 v84, v93
	s_waitcnt vmcnt(3)
	ds_write_b128 v190, v[162:165]
	s_waitcnt vmcnt(2)
	ds_write_b128 v188, v[158:161]
	v_add_f32_e32 v83, v82, v131
	v_cvt_pk_bf16_f32 v131, v82, v84
	v_add_f32_e32 v83, v84, v83
	s_waitcnt lgkmcnt(4)
	v_mfma_f32_32x32x16_bf16 v[66:81], v[202:205], v[122:125], v[66:81]
	v_exp_f32_e32 v82, v94
	s_nop 0
	v_add_f32_e32 v83, v82, v83
	s_waitcnt lgkmcnt(3)
	v_mfma_f32_32x32x16_bf16 v[98:113], v[182:185], v[126:129], v[98:113]
	v_exp_f32_e32 v84, v95
	s_nop 0
	v_cvt_pk_bf16_f32 v132, v82, v84
	v_exp_f32_e32 v82, v96
	v_add_f32_e32 v83, v84, v83
	v_add_u32_e32 v84, s79, v176
	s_waitcnt vmcnt(1)
	ds_write_b128 v84, v[150:153] offset:51200
	v_add_u32_e32 v84, s79, v178
	v_add_f32_e32 v83, v82, v83
	s_waitcnt vmcnt(0)
	ds_write_b128 v84, v[154:157] offset:51200
	s_cmpk_lt_u32 s76, 0x7f
	s_cselect_b32 s84, s67, 0
	s_cselect_b32 s98, 0x4d000, 0
	s_add_u32 s84, s84, s88
	s_add_u32 s98, s98, s88
	s_add_u32 s84, s8, s84
	s_addc_u32 s85, s9, 0
	s_add_u32 s98, s8, s98
	s_addc_u32 s99, s9, 0
	s_waitcnt lgkmcnt(4)
	v_mfma_f32_32x32x16_bf16 v[66:81], v[86:89], v[126:129], v[66:81]
	v_exp_f32_e32 v84, v97
	s_nop 0
	v_add_f32_e32 v163, v84, v83
	v_cvt_pk_bf16_f32 v133, v82, v84
	v_add_u32_e32 v82, s78, v192
	ds_read_b64_tr_b16 v[158:159], v82 offset:51200
	ds_read_b64_tr_b16 v[154:155], v82 offset:51264
	ds_read_b64_tr_b16 v[150:151], v82 offset:51328
	ds_read_b64_tr_b16 v[146:147], v82 offset:51392
	ds_read_b64_tr_b16 v[160:161], v82 offset:53760
	ds_read_b64_tr_b16 v[156:157], v82 offset:53824
	ds_read_b64_tr_b16 v[152:153], v82 offset:53888
	ds_read_b64_tr_b16 v[148:149], v82 offset:53952
	s_and_b64 s[0:1], s[0:1], s[36:37]
	s_andn2_b64 vcc, exec, s[0:1]
	s_cbranch_vccnz .LBB0_994
	v_add_u32_e32 v82, 0xc0, v200
	v_med3_i32 v83, v82, 0, v216
	v_med3_i32 v82, v82, s46, v217
	v_lshl_add_u32 v84, v82, 2, s15
	v_add_u32_e32 v82, 0xc1, v200
	v_med3_i32 v85, v82, 0, v216
	v_med3_i32 v82, v82, s46, v217
	v_lshl_add_u32 v86, v82, 2, s15
	v_add_u32_e32 v82, 0xc2, v200
	v_med3_i32 v87, v82, 0, v216
	v_med3_i32 v82, v82, s46, v217
	v_lshl_add_u32 v88, v82, 2, s15
	v_add_u32_e32 v82, 0xc3, v200
	v_med3_i32 v89, v82, 0, v216
	v_med3_i32 v82, v82, s46, v217
	v_lshl_add_u32 v83, v83, 2, s15
	v_lshl_add_u32 v85, v85, 2, s15
	v_lshl_add_u32 v87, v87, 2, s15
	v_lshl_add_u32 v89, v89, 2, s15
	v_lshl_add_u32 v90, v82, 2, s15
	ds_read_b32 v82, v83
	ds_read_b32 v84, v84 offset:128
	ds_read_b32 v83, v85
	ds_read_b32 v85, v86 offset:128
	ds_read_b32 v86, v87
	ds_read_b32 v88, v88 offset:128
	ds_read_b32 v87, v89
	ds_read_b32 v89, v90 offset:128
	v_add_u32_e32 v90, 0xc8, v200
	v_med3_i32 v91, v90, 0, v216
	v_med3_i32 v90, v90, s46, v217
	v_lshl_add_u32 v92, v90, 2, s15
	v_add_u32_e32 v90, 0xc9, v200
	v_med3_i32 v93, v90, 0, v216
	v_med3_i32 v90, v90, s46, v217
	v_lshl_add_u32 v94, v90, 2, s15
	v_add_u32_e32 v90, 0xca, v200
	v_med3_i32 v95, v90, 0, v216
	v_med3_i32 v90, v90, s46, v217
	v_add_u32_e32 v165, 0xd1, v200
	v_lshl_add_u32 v96, v90, 2, s15
	v_add_u32_e32 v90, 0xcb, v200
	v_med3_i32 v182, v165, 0, v216
	v_med3_i32 v165, v165, s46, v217
	v_med3_i32 v97, v90, 0, v216
	v_med3_i32 v90, v90, s46, v217
	v_lshl_add_u32 v184, v165, 2, s15
	v_add_u32_e32 v165, 0xd2, v200
	v_lshl_add_u32 v91, v91, 2, s15
	v_lshl_add_u32 v93, v93, 2, s15
	v_lshl_add_u32 v95, v95, 2, s15
	v_lshl_add_u32 v97, v97, 2, s15
	v_lshl_add_u32 v162, v90, 2, s15
	v_lshl_add_u32 v183, v182, 2, s15
	v_med3_i32 v182, v165, 0, v216
	v_med3_i32 v165, v165, s46, v217
	ds_read_b32 v90, v91
	ds_read_b32 v92, v92 offset:128
	ds_read_b32 v91, v93
	ds_read_b32 v93, v94 offset:128
	ds_read_b32 v94, v95
	ds_read_b32 v96, v96 offset:128
	ds_read_b32 v95, v97
	ds_read_b32 v97, v162 offset:128
	v_add_u32_e32 v162, 0xd0, v200
	v_lshl_add_u32 v201, v165, 2, s15
	v_add_u32_e32 v165, 0xd3, v200
	v_med3_i32 v164, v162, 0, v216
	v_lshl_add_u32 v185, v182, 2, s15
	v_med3_i32 v182, v165, 0, v216
	v_med3_i32 v165, v165, s46, v217
	v_med3_i32 v162, v162, s46, v217
	v_lshl_add_u32 v164, v164, 2, s15
	v_lshl_add_u32 v203, v182, 2, s15
	v_lshl_add_u32 v204, v165, 2, s15
	v_lshl_add_u32 v162, v162, 2, s15
	ds_read_b32 v164, v164
	ds_read_b32 v182, v162 offset:128
	ds_read_b32 v165, v183
	ds_read_b32 v183, v184 offset:128
	ds_read_b32 v184, v185
	ds_read_b32 v202, v201 offset:128
	ds_read_b32 v185, v203
	ds_read_b32 v203, v204 offset:128
	v_add_u32_e32 v204, 0xd9, v200
	v_med3_i32 v205, v204, 0, v216
	v_med3_i32 v204, v204, s46, v217
	v_lshl_add_u32 v210, v204, 2, s15
	v_add_u32_e32 v204, 0xda, v200
	v_add_u32_e32 v162, 0xd8, v200
	v_med3_i32 v206, v204, 0, v216
	v_med3_i32 v204, v204, s46, v217
	v_add_u32_e32 v200, 0xdb, v200
	v_med3_i32 v201, v162, 0, v216
	v_lshl_add_u32 v208, v204, 2, s15
	v_med3_i32 v204, v200, 0, v216
	v_med3_i32 v200, v200, s46, v217
	v_med3_i32 v162, v162, s46, v217
	v_lshl_add_u32 v201, v201, 2, s15
	v_lshl_add_u32 v205, v205, 2, s15
	v_lshl_add_u32 v206, v206, 2, s15
	v_lshl_add_u32 v207, v204, 2, s15
	v_lshl_add_u32 v209, v200, 2, s15
	v_lshl_add_u32 v162, v162, 2, s15
	ds_read_b32 v200, v201
	ds_read_b32 v204, v162 offset:128
	ds_read_b32 v206, v206
	ds_read_b32 v207, v207
	ds_read_b32 v201, v205
	ds_read_b32 v209, v209 offset:128
	ds_read_b32 v208, v208 offset:128
	ds_read_b32 v205, v210 offset:128
	s_waitcnt lgkmcnt(4)
	v_pk_add_f32 v[112:113], v[112:113], v[206:207]
	s_waitcnt lgkmcnt(3)
	v_pk_add_f32 v[110:111], v[110:111], v[200:201]
	v_pk_add_f32 v[108:109], v[108:109], v[184:185]
	v_pk_add_f32 v[106:107], v[106:107], v[164:165]
	v_pk_add_f32 v[104:105], v[104:105], v[94:95]
	v_pk_add_f32 v[102:103], v[102:103], v[90:91]
	v_pk_add_f32 v[100:101], v[100:101], v[86:87]
	v_pk_add_f32 v[98:99], v[98:99], v[82:83]
	s_waitcnt lgkmcnt(1)
	v_pk_add_f32 v[80:81], v[80:81], v[208:209]
	s_waitcnt lgkmcnt(0)
	v_pk_add_f32 v[78:79], v[78:79], v[204:205]
	v_pk_add_f32 v[76:77], v[76:77], v[202:203]
	v_pk_add_f32 v[74:75], v[74:75], v[182:183]
	v_pk_add_f32 v[72:73], v[72:73], v[96:97]
	v_pk_add_f32 v[70:71], v[70:71], v[92:93]
	v_pk_add_f32 v[68:69], v[68:69], v[88:89]
	v_pk_add_f32 v[66:67], v[66:67], v[84:85]

.LBB0_997:
	v_cmp_neq_f32_e32 vcc, v82, v228
	s_cbranch_vccz .Lnc_b_skip
	v_mov_b32_e32 v228, v82
	v_mov_b32_e32 v229, v82
	v_mov_b32_e32 v230, v82
	v_mov_b32_e32 v231, v82
	v_mov_b32_e32 v232, v82
	v_mov_b32_e32 v233, v82
	v_mov_b32_e32 v234, v82
	v_mov_b32_e32 v235, v82
	v_mov_b32_e32 v236, v82
	v_mov_b32_e32 v237, v82
	v_mov_b32_e32 v238, v82
	v_mov_b32_e32 v239, v82
	v_mov_b32_e32 v240, v82
	v_mov_b32_e32 v241, v82
	v_mov_b32_e32 v242, v82
	v_mov_b32_e32 v243, v82
